# fused final epilogue: the 128 sample rows are normalised by workgroups 128..143 (no skinny unit in this phase) instead of workgroups 0..15
# speedup vs baseline: 1.0100x; 1.0100x over previous
; __device__ __forceinline__ void epi_final(f32x4 (&acc)[2][2][4][2], const Unit& u, int wr, int wc, int fr, int fq, const EpiArgs& E, LAS float* rt) {
;     ...
;     if (E.scnt && blockIdx.x * 8 < MS) {
;         if (wid == 0) { unsigned sp = 0;
;             while ((unsigned)__builtin_amdgcn_readfirstlane(__hip_atomic_load(E.scnt, __ATOMIC_RELAXED, __HIP_MEMORY_SCOPE_AGENT)) < 8u * 128u) { __builtin_amdgcn_s_sleep(2); if (++sp > (1u << 20)) break; } }
.LBB0_1427:
	s_or_b64 exec, exec, s[4:5]
	s_sub_u32 s4, s2, 0x80
	s_and_b32 s4, s4, -16
	s_cmp_lg_u32 s4, 0
	s_cbranch_scc1 .LBB0_1434
	s_cmp_gt_u32 s9, 63
	s_cbranch_scc1 .LBB0_1433
	s_mov_b32 s6, 0x100001
	v_mov_b32_e32 v152, 0
	s_branch .LBB0_1431

; __device__ __forceinline__ float bflo(unsigned u) { return __uint_as_float(u << 16); }
; __device__ __forceinline__ float bfhi(unsigned u) { return __uint_as_float(u & 0xffff0000u); }
; __device__ __forceinline__ void epi_final(f32x4 (&acc)[2][2][4][2], const Unit& u, int wr, int wc, int fr, int fq, const EpiArgs& E, LAS float* rt) {
;     ...
;         __syncthreads();
;         const int srow = MP + blockIdx.x * 8 + wid;
;         float s = __uint_as_float(__hip_atomic_load((const unsigned*)E.stOut + (size_t)srow * 16 + (lane & 15), __ATOMIC_RELAXED, __HIP_MEMORY_SCOPE_AGENT));
;         s += __shfl_xor(s, 1); s += __shfl_xor(s, 2); s += __shfl_xor(s, 4); s += __shfl_xor(s, 8);
;         const float sr = rsqrtf(s * (1.0f / 1024.0f) + EPS);
;         const unsigned long long* sxb = (const unsigned long long*)(E.res + (size_t)srow * 1024);
; #pragma unroll
;         for (int i = 0; i < 4; ++i) { const int c = i * 256 + lane * 4; const unsigned long long q = __hip_atomic_load(sxb + (c >> 2), __ATOMIC_RELAXED, __HIP_MEMORY_SCOPE_AGENT);
;             const unsigned qx = (unsigned)q, qy = (unsigned)(q >> 32); const f32x4 v = {bflo(qx), bfhi(qx), bflo(qy), bfhi(qy)};
;             const f32x4 gg = *(const f32x4*)(E.gfin + c); *(f32x4*)(E.yout + (size_t)srow * 1024 + c) = v * sr * gg; }
.LBB0_1433:
	s_lshr_b32 s4, s9, 6
	s_sub_u32 s5, s2, 0x80
	s_lshl_b32 s5, s5, 3
	s_add_i32 s4, s4, s5
	s_add_i32 s6, s4, 0x4000
	s_mov_b32 s7, 0
	s_lshl_b64 s[4:5], s[6:7], 6
	s_add_u32 s4, s10, s4
	s_addc_u32 s5, s11, s5
	s_waitcnt lgkmcnt(0)
	s_barrier
	global_load_dword v156, v151, s[4:5] sc1
	s_lshl_b64 s[4:5], s[6:7], 11
	s_add_u32 s4, s62, s4
	v_lshlrev_b32_e32 v157, 3, v150
	s_addc_u32 s5, s63, s5
	global_load_dwordx2 v[154:155], v157, s[4:5] sc1
	v_lshlrev_b32_e32 v158, 4, v150
	global_load_dwordx4 v[150:153], v158, s[24:25]
	v_xor_b32_e32 v159, 1, v148
	v_cmp_lt_i32_e32 vcc, v159, v149
	v_xor_b32_e32 v160, 2, v148
	v_xor_b32_e32 v161, 4, v148
	v_cndmask_b32_e32 v159, v148, v159, vcc
	v_lshlrev_b32_e32 v159, 2, v159
	v_cmp_lt_i32_e32 vcc, v160, v149
	v_xor_b32_e32 v162, 8, v148
	v_mov_b32_e32 v163, 0x358637bd
	v_cndmask_b32_e32 v160, v148, v160, vcc
	v_lshlrev_b32_e32 v160, 2, v160
	v_cmp_lt_i32_e32 vcc, v161, v149
	s_mov_b32 s18, 0x800000
	s_lshl_b64 s[6:7], s[6:7], 12
	s_add_u32 s6, s28, s6
	s_addc_u32 s7, s29, s7
	s_waitcnt vmcnt(2)
	ds_bpermute_b32 v159, v159, v156
	s_waitcnt lgkmcnt(0)
	v_add_f32_e32 v156, v159, v156
	ds_bpermute_b32 v159, v160, v156
	v_cndmask_b32_e32 v160, v148, v161, vcc
	v_lshlrev_b32_e32 v160, 2, v160
	v_cmp_lt_i32_e32 vcc, v162, v149
	s_waitcnt lgkmcnt(0)
	v_add_f32_e32 v156, v156, v159
	ds_bpermute_b32 v159, v160, v156
	v_cndmask_b32_e32 v148, v148, v162, vcc
	v_lshlrev_b32_e32 v148, 2, v148
	v_or_b32_e32 v160, 0x200, v157
	s_waitcnt lgkmcnt(0)
	v_add_f32_e32 v149, v156, v159
	ds_bpermute_b32 v156, v148, v149
	s_waitcnt vmcnt(1)
	v_lshlrev_b32_e32 v148, 16, v154
	s_waitcnt lgkmcnt(0)
	v_add_f32_e32 v149, v149, v156
	v_fmac_f32_e32 v163, 0x3a800000, v149
	v_mul_f32_e32 v149, 0x4b800000, v163
	v_cmp_gt_f32_e32 vcc, s18, v163
	s_nop 1
	v_cndmask_b32_e32 v149, v163, v149, vcc
	v_rsq_f32_e32 v156, v149
	v_and_b32_e32 v149, 0xffff0000, v154
	v_lshlrev_b32_e32 v154, 16, v155
	v_and_b32_e32 v155, 0xffff0000, v155
	v_mul_f32_e32 v159, 0x45800000, v156
	v_cndmask_b32_e32 v156, v156, v159, vcc
	v_pk_mul_f32 v[148:149], v[156:157], v[148:149] op_sel_hi:[0,1]
	v_pk_mul_f32 v[154:155], v[156:157], v[154:155] op_sel_hi:[0,1]
	s_waitcnt vmcnt(0)
	v_pk_mul_f32 v[152:153], v[152:153], v[154:155]
	v_pk_mul_f32 v[150:151], v[150:151], v[148:149]
	global_store_dwordx4 v158, v[150:153], s[6:7]
	global_load_dwordx2 v[152:153], v160, s[4:5] sc1
	s_nop 0
	global_load_dwordx4 v[148:151], v158, s[24:25] offset:1024
	v_or_b32_e32 v159, 0x400, v157
	s_waitcnt vmcnt(1)
	v_lshlrev_b32_e32 v154, 16, v152
	v_and_b32_e32 v155, 0xffff0000, v152
	v_lshlrev_b32_e32 v152, 16, v153
	v_and_b32_e32 v153, 0xffff0000, v153
	v_pk_mul_f32 v[154:155], v[156:157], v[154:155] op_sel_hi:[0,1]
	v_pk_mul_f32 v[152:153], v[156:157], v[152:153] op_sel_hi:[0,1]
	s_waitcnt vmcnt(0)
	v_pk_mul_f32 v[150:151], v[150:151], v[152:153]
	v_pk_mul_f32 v[148:149], v[148:149], v[154:155]
	global_store_dwordx4 v158, v[148:151], s[6:7] offset:1024
	global_load_dwordx2 v[152:153], v159, s[4:5] sc1
	s_nop 0
	global_load_dwordx4 v[148:151], v158, s[24:25] offset:2048
	v_or_b32_e32 v157, 0x600, v157
	s_waitcnt vmcnt(1)
	v_lshlrev_b32_e32 v154, 16, v152
	v_and_b32_e32 v155, 0xffff0000, v152
	v_lshlrev_b32_e32 v152, 16, v153
	v_and_b32_e32 v153, 0xffff0000, v153
	v_pk_mul_f32 v[154:155], v[156:157], v[154:155] op_sel_hi:[0,1]
	v_pk_mul_f32 v[152:153], v[156:157], v[152:153] op_sel_hi:[0,1]
	s_waitcnt vmcnt(0)
	v_pk_mul_f32 v[150:151], v[150:151], v[152:153]
	v_pk_mul_f32 v[148:149], v[148:149], v[154:155]
	global_store_dwordx4 v158, v[148:151], s[6:7] offset:2048
	global_load_dwordx2 v[152:153], v157, s[4:5] sc1
	s_nop 0
	global_load_dwordx4 v[148:151], v158, s[24:25] offset:3072
	s_waitcnt vmcnt(1)
	v_lshlrev_b32_e32 v154, 16, v152
	v_and_b32_e32 v155, 0xffff0000, v152
	v_lshlrev_b32_e32 v152, 16, v153
	v_and_b32_e32 v153, 0xffff0000, v153
	v_pk_mul_f32 v[154:155], v[156:157], v[154:155] op_sel_hi:[0,1]
	v_pk_mul_f32 v[152:153], v[156:157], v[152:153] op_sel_hi:[0,1]
	s_waitcnt vmcnt(0)
	v_pk_mul_f32 v[150:151], v[150:151], v[152:153]
	v_pk_mul_f32 v[148:149], v[148:149], v[154:155]
	global_store_dwordx4 v158, v[148:151], s[6:7] offset:3072
